# scan split into 128 half tasks (2 state elements per thread), hand-written 3-buffer scan loop; queue decode remapped
# baseline (speedup 1.0000x reference)
; __device__ __forceinline__ void scan_task(const Params& p, int l, int j, LAS unsigned char* lds) {
;     ...
;     float* go = p.out + OFF_GSP + ((size_t)l * 4 + h) * 32768 + dk * 256 + dv;
; #pragma unroll
;     for (int i = 0; i < 4; ++i) go[i * 256] = S[i];
.LBB0_590:
	s_xor_b64 s[14:15], s[0:1], -1
	s_mov_b32 s22, 0
	s_branch .LBB0_594
.LBB0_592:
	s_mov_b32 s2, 0
	s_mov_b32 s93, s23

; __global__ void __launch_bounds__(NTHREADS) fwd_megakernel(Params p) {
;     ...
;             for (int n = 0;; ++n) {
;                 int code;
;                 if (sub == 0) {
;                     const int q = queue_next(qc, qslot);
;                     if (q >= 496) break;
;                     code = (q < 64) ? q : (q < 96 ? 608 + (q - 64) : (q < 128 ? 640 + (q - 96) : (q < 160 ? 64 + 512 + (q - 128) : 64 + (q - 160))));
.LBB0_617:
	s_or_b64 exec, exec, s[0:1]
	s_add_i32 s0, 0, 0x20000
	v_mov_b32_e32 v0, s0
	s_waitcnt lgkmcnt(0)
	s_barrier
	ds_read_b32 v0, v0
	s_movk_i32 s0, 0x1ef
	s_mov_b32 s2, 20
	s_waitcnt lgkmcnt(0)
	v_cmp_gt_i32_e32 vcc, 0x80, v0
	v_lshrrev_b32_e32 v2, 1, v0
	v_add_u32_e32 v3, 0xffffffc0, v0
	v_cndmask_b32_e32 v0, v3, v2, vcc
	v_cmp_lt_i32_e32 vcc, s0, v0
	s_movk_i32 s0, 0x1f0
	v_readfirstlane_b32 s6, v0
	v_cmp_gt_i32_e64 s[0:1], s0, v0
	s_cbranch_vccnz .LBB0_633
	s_cmp_lt_i32 s6, 64
	s_cbranch_scc1 .LBB0_632
	s_cmpk_gt_u32 s6, 0x5f
	s_mov_b64 s[16:17], -1
	s_cbranch_scc0 .LBB0_629
	s_cmpk_gt_u32 s6, 0x7f
	s_cbranch_scc0 .LBB0_626
	s_cmpk_gt_u32 s6, 0x9f
	s_cbranch_scc0 .LBB0_623
	s_add_i32 s2, s6, 0xffffffa0
	s_mov_b64 s[16:17], 0

; #define LAS __attribute__((address_space(3)))
; #define SCAN_LOAD(uv, cb) do { _Pragma("unroll") for (int i = 0; i < 16; ++i) uv[i] = *(const u32x2*)(ut + (size_t)((cb) + i) * 131072); } while (0)
; __device__ __forceinline__ void scan_task(const Params& p, int l, int j, LAS unsigned char* lds) {
;     unsigned char* ws = p.ws;
;     int tid = threadIdx.x; asm volatile("" : "+v"(tid)); asm volatile("" : "+s"(l));
;     const int e = j * 2048 + tid * 4;
;     const int h = e >> 15, dk = e & 127, dv = (e >> 7) & 255;
;     const u16* ut = (const u16*)(ws + WS_UT) + e; u16* sp = (u16*)(ws + WS_SP) + e;
;     LAS float* dl = (LAS float*)lds;
;     {
;         const float* dsrc = (const float*)(ws + WS_DEC) + h * 128;
; #pragma unroll
;         for (int i = 0; i < 16; ++i) { const int q = tid + i * 512, c = q >> 5, d4 = (q & 31) * 4; *(LAS f32x4*)(dl + c * 128 + d4) = *(const f32x4*)(dsrc + (size_t)c * 512 + d4); }
;     }
;     f32x4 S = (f32x4){0.f, 0.f, 0.f, 0.f};
;     u32x2 uvA[16], uvB[16];
;     ...
;     SCAN_LOAD(uvA, 0);
;     __syncthreads();
.LBB0_770:
	s_andn2_b64 vcc, exec, s[0:1]
	s_cbranch_vccnz .LBB0_592
	v_mov_b32_e32 v9, v200
	v_readlane_b32 s6, v254, 36
	v_lshlrev_b32_e32 v0, 2, v9
	v_lshl_add_u32 v6, s23, 11, v0
	v_ashrrev_i32_e32 v8, 15, v6
	s_waitcnt lgkmcnt(0)
	v_lshlrev_b32_e32 v2, 7, v8
	v_and_b32_e32 v82, 0x7c, v0
	v_ashrrev_i32_e32 v3, 31, v2
	v_readlane_b32 s7, v254, 37
	v_ashrrev_i32_e32 v4, 5, v9
	v_lshlrev_b32_e32 v0, 2, v82
	v_lshl_add_u64 v[2:3], v[2:3], 2, s[6:7]
	v_ashrrev_i32_e32 v5, 31, v4
	v_lshl_add_u64 v[2:3], v[2:3], 0, v[0:1]
	v_lshlrev_b64 v[10:11], 11, v[4:5]
	s_mov_b32 s0, s31
	v_lshl_add_u64 v[10:11], v[2:3], 0, v[10:11]
	v_add_u32_e32 v0, 0, v0
	v_lshl_add_u32 v4, v4, 9, v0
	v_ashrrev_i32_e32 v7, 31, v6
	s_mov_b32 s1, 0x40000
	s_mov_b32 s2, 0x80000
	v_readlane_b32 s6, v252, 37
	v_readlane_b32 s7, v252, 38
	s_mov_b64 s[98:99], 0x8000
	v_mov_b32_e32 v42, v10
	v_mov_b32_e32 v43, v11
	global_load_dwordx4 v[10:13], v[42:43], off
	v_lshl_add_u64 v[42:43], v[42:43], 0, s[98:99]
	global_load_dwordx4 v[14:17], v[42:43], off
	v_lshl_add_u64 v[42:43], v[42:43], 0, s[98:99]
	global_load_dwordx4 v[18:21], v[42:43], off
	v_lshl_add_u64 v[42:43], v[42:43], 0, s[98:99]
	global_load_dwordx4 v[22:25], v[42:43], off
	v_lshl_add_u64 v[42:43], v[42:43], 0, s[98:99]
	global_load_dwordx4 v[26:29], v[42:43], off
	v_lshl_add_u64 v[42:43], v[42:43], 0, s[98:99]
	global_load_dwordx4 v[30:33], v[42:43], off
	v_lshl_add_u64 v[42:43], v[42:43], 0, s[98:99]
	global_load_dwordx4 v[34:37], v[42:43], off
	v_lshl_add_u64 v[42:43], v[42:43], 0, s[98:99]
	global_load_dwordx4 v[38:41], v[42:43], off
	v_lshl_add_u64 v[42:43], v[42:43], 0, s[98:99]
	global_load_dwordx4 v[46:49], v[42:43], off
	v_lshl_add_u64 v[42:43], v[42:43], 0, s[98:99]
	global_load_dwordx4 v[50:53], v[42:43], off
	v_lshl_add_u64 v[42:43], v[42:43], 0, s[98:99]
	global_load_dwordx4 v[54:57], v[42:43], off
	v_lshl_add_u64 v[42:43], v[42:43], 0, s[98:99]
	global_load_dwordx4 v[58:61], v[42:43], off
	v_lshl_add_u64 v[42:43], v[42:43], 0, s[98:99]
	global_load_dwordx4 v[62:65], v[42:43], off
	v_lshl_add_u64 v[42:43], v[42:43], 0, s[98:99]
	global_load_dwordx4 v[66:69], v[42:43], off
	v_lshl_add_u64 v[42:43], v[42:43], 0, s[98:99]
	global_load_dwordx4 v[70:73], v[42:43], off
	v_lshl_add_u64 v[42:43], v[42:43], 0, s[98:99]
	global_load_dwordx4 v[42:45], v[42:43], off
	v_add_u32_e32 v5, 0x10000, v4
	s_waitcnt vmcnt(15)
	ds_write_b128 v4, v[10:13]
	s_waitcnt vmcnt(14)
	ds_write_b128 v4, v[14:17] offset:8192
	s_waitcnt vmcnt(13)
	ds_write_b128 v4, v[18:21] offset:16384
	s_waitcnt vmcnt(12)
	ds_write_b128 v4, v[22:25] offset:24576
	s_waitcnt vmcnt(11)
	ds_write_b128 v4, v[26:29] offset:32768
	s_waitcnt vmcnt(10)
	ds_write_b128 v4, v[30:33] offset:40960
	s_waitcnt vmcnt(9)
	ds_write_b128 v4, v[34:37] offset:49152
	s_waitcnt vmcnt(8)
	ds_write_b128 v4, v[38:41] offset:57344
	s_waitcnt vmcnt(7)
	ds_write_b128 v5, v[46:49]
	s_waitcnt vmcnt(6)
	ds_write_b128 v5, v[50:53] offset:8192
	s_waitcnt vmcnt(5)
	ds_write_b128 v5, v[54:57] offset:16384
	s_waitcnt vmcnt(4)
	ds_write_b128 v5, v[58:61] offset:24576
	s_waitcnt vmcnt(3)
	ds_write_b128 v5, v[62:65] offset:32768
	s_waitcnt vmcnt(2)
	ds_write_b128 v5, v[66:69] offset:40960
	s_waitcnt vmcnt(1)
	ds_write_b128 v5, v[70:73] offset:49152
	s_waitcnt vmcnt(0)
	ds_write_b128 v5, v[42:45] offset:57344
	v_mov_b32_e32 v4, 0x20000
	ds_read_b32 v4, v4
	s_waitcnt lgkmcnt(0)
	v_readfirstlane_b32 s2, v4
	s_nop 3
	s_and_b32 s2, s2, 1
	s_lshl_b32 s0, s23, 12
	s_lshl_b32 s1, s2, 11
	s_add_u32 s0, s0, s1
	v_lshlrev_b32_e32 v10, 2, v200
	v_add_u32_e32 v10, s0, v10
	v_add_u32_e32 v11, 0x40000, v10
	v_add_u32_e32 v12, 0x40000, v11
	v_add_u32_e32 v13, 0x40000, v12
	v_add_u32_e32 v14, 0x40000, v13
	v_add_u32_e32 v15, 0x40000, v14
	v_add_u32_e32 v16, 0x40000, v15
	v_add_u32_e32 v17, 0x40000, v16
	v_add_u32_e32 v18, 0x40000, v17
	v_add_u32_e32 v19, 0x40000, v18
	v_add_u32_e32 v20, 0x40000, v19
	v_add_u32_e32 v21, 0x40000, v20
	v_add_u32_e32 v22, 0x40000, v21
	v_add_u32_e32 v23, 0x40000, v22
	v_add_u32_e32 v24, 0x40000, v23
	v_add_u32_e32 v25, 0x40000, v24
	v_and_b32_e32 v9, 63, v200
	v_lshlrev_b32_e32 v9, 3, v9
	s_mov_b64 s[16:17], s[66:67]
	s_add_u32 s6, s58, 0x25308000
	s_addc_u32 s7, s59, 0
	v_mov_b32_e32 v2, 0
	v_mov_b32_e32 v3, 0
	global_load_dword v26, v10, s[16:17]
	global_load_dword v27, v11, s[16:17]
	global_load_dword v28, v12, s[16:17]
	global_load_dword v29, v13, s[16:17]
	global_load_dword v30, v14, s[16:17]
	global_load_dword v31, v15, s[16:17]
	global_load_dword v32, v16, s[16:17]
	global_load_dword v33, v17, s[16:17]
	global_load_dword v34, v18, s[16:17]
	global_load_dword v35, v19, s[16:17]
	global_load_dword v36, v20, s[16:17]
	global_load_dword v37, v21, s[16:17]
	global_load_dword v38, v22, s[16:17]
	global_load_dword v39, v23, s[16:17]
	global_load_dword v40, v24, s[16:17]
	global_load_dword v41, v25, s[16:17]
	s_add_u32 s16, s16, 0x400000
	s_addc_u32 s17, s17, 0
	global_load_dword v42, v10, s[16:17]
	global_load_dword v43, v11, s[16:17]
	global_load_dword v44, v12, s[16:17]
	global_load_dword v45, v13, s[16:17]
	global_load_dword v46, v14, s[16:17]
	global_load_dword v47, v15, s[16:17]
	global_load_dword v48, v16, s[16:17]
	global_load_dword v49, v17, s[16:17]
	global_load_dword v50, v18, s[16:17]
	global_load_dword v51, v19, s[16:17]
	global_load_dword v52, v20, s[16:17]
	global_load_dword v53, v21, s[16:17]
	global_load_dword v54, v22, s[16:17]
	global_load_dword v55, v23, s[16:17]
	global_load_dword v56, v24, s[16:17]
	global_load_dword v57, v25, s[16:17]
	s_add_u32 s16, s16, 0x400000
	s_addc_u32 s17, s17, 0
	s_waitcnt lgkmcnt(0)
	s_barrier
; #define SCAN_LOAD(uv, cb) do { _Pragma("unroll") for (int i = 0; i < 16; ++i) uv[i] = *(const u32x2*)(ut + (size_t)((cb) + i) * 131072); } while (0)
; __device__ __forceinline__ void scan_task(const Params& p, int l, int j, LAS unsigned char* lds) {
;     ...
;     SCAN_LOAD(uvA, 0);
;     __syncthreads();
;     for (int c0 = 0; c0 < 256; c0 += 32) {
;         SCAN_LOAD(uvB, c0 + 16);
;         SCAN_STEP(uvA, c0);
	global_load_dword v58, v10, s[16:17]
	global_load_dword v59, v11, s[16:17]
	global_load_dword v60, v12, s[16:17]
	global_load_dword v61, v13, s[16:17]
	global_load_dword v62, v14, s[16:17]
	global_load_dword v63, v15, s[16:17]
	global_load_dword v64, v16, s[16:17]
	global_load_dword v65, v17, s[16:17]
	global_load_dword v66, v18, s[16:17]
	global_load_dword v67, v19, s[16:17]
	global_load_dword v68, v20, s[16:17]
	global_load_dword v69, v21, s[16:17]
	global_load_dword v70, v22, s[16:17]
	global_load_dword v71, v23, s[16:17]
	global_load_dword v72, v24, s[16:17]
	global_load_dword v73, v25, s[16:17]
	s_add_u32 s16, s16, 0x400000
	s_addc_u32 s17, s17, 0
	ds_read_b64 v[100:101], v9
	ds_read_b64 v[102:103], v9 offset:512
	ds_read_b64 v[104:105], v9 offset:1024
	ds_read_b64 v[106:107], v9 offset:1536
	ds_read_b64 v[108:109], v9 offset:2048
	ds_read_b64 v[110:111], v9 offset:2560
	ds_read_b64 v[112:113], v9 offset:3072
	ds_read_b64 v[114:115], v9 offset:3584
	s_waitcnt vmcnt(32)
	v_cvt_pk_bf16_f32 v116, v2, v3
	global_store_dword v10, v116, s[6:7]
	v_lshlrev_b32_e32 v118, 16, v26
	v_and_b32_e32 v119, 0xffff0000, v26
	s_waitcnt lgkmcnt(7)
	v_pk_fma_f32 v[2:3], v[100:101], v[2:3], v[118:119]
	ds_read_b64 v[100:101], v9 offset:4096
	v_cvt_pk_bf16_f32 v117, v2, v3
	global_store_dword v11, v117, s[6:7]
	v_lshlrev_b32_e32 v118, 16, v27
	v_and_b32_e32 v119, 0xffff0000, v27
	s_waitcnt lgkmcnt(7)
	v_pk_fma_f32 v[2:3], v[102:103], v[2:3], v[118:119]
	ds_read_b64 v[102:103], v9 offset:4608
	v_cvt_pk_bf16_f32 v116, v2, v3
	global_store_dword v12, v116, s[6:7]
	v_lshlrev_b32_e32 v118, 16, v28
	v_and_b32_e32 v119, 0xffff0000, v28
	s_waitcnt lgkmcnt(7)
	v_pk_fma_f32 v[2:3], v[104:105], v[2:3], v[118:119]
	ds_read_b64 v[104:105], v9 offset:5120
	v_cvt_pk_bf16_f32 v117, v2, v3
	global_store_dword v13, v117, s[6:7]
	v_lshlrev_b32_e32 v118, 16, v29
	v_and_b32_e32 v119, 0xffff0000, v29
	s_waitcnt lgkmcnt(7)
	v_pk_fma_f32 v[2:3], v[106:107], v[2:3], v[118:119]
	ds_read_b64 v[106:107], v9 offset:5632
	v_cvt_pk_bf16_f32 v116, v2, v3
	global_store_dword v14, v116, s[6:7]
	v_lshlrev_b32_e32 v118, 16, v30
	v_and_b32_e32 v119, 0xffff0000, v30
	s_waitcnt lgkmcnt(7)
	v_pk_fma_f32 v[2:3], v[108:109], v[2:3], v[118:119]
	ds_read_b64 v[108:109], v9 offset:6144
	v_cvt_pk_bf16_f32 v117, v2, v3
	global_store_dword v15, v117, s[6:7]
	v_lshlrev_b32_e32 v118, 16, v31
	v_and_b32_e32 v119, 0xffff0000, v31
	s_waitcnt lgkmcnt(7)
	v_pk_fma_f32 v[2:3], v[110:111], v[2:3], v[118:119]
	ds_read_b64 v[110:111], v9 offset:6656
	v_cvt_pk_bf16_f32 v116, v2, v3
	global_store_dword v16, v116, s[6:7]
	v_lshlrev_b32_e32 v118, 16, v32
	v_and_b32_e32 v119, 0xffff0000, v32
	s_waitcnt lgkmcnt(7)
	v_pk_fma_f32 v[2:3], v[112:113], v[2:3], v[118:119]
	ds_read_b64 v[112:113], v9 offset:7168
	v_cvt_pk_bf16_f32 v117, v2, v3
	global_store_dword v17, v117, s[6:7]
	v_lshlrev_b32_e32 v118, 16, v33
	v_and_b32_e32 v119, 0xffff0000, v33
	s_waitcnt lgkmcnt(7)
	v_pk_fma_f32 v[2:3], v[114:115], v[2:3], v[118:119]
	ds_read_b64 v[114:115], v9 offset:7680
	v_cvt_pk_bf16_f32 v116, v2, v3
	global_store_dword v18, v116, s[6:7]
	v_lshlrev_b32_e32 v118, 16, v34
	v_and_b32_e32 v119, 0xffff0000, v34
	s_waitcnt lgkmcnt(7)
	v_pk_fma_f32 v[2:3], v[100:101], v[2:3], v[118:119]
	v_cvt_pk_bf16_f32 v117, v2, v3
	global_store_dword v19, v117, s[6:7]
	v_lshlrev_b32_e32 v118, 16, v35
	v_and_b32_e32 v119, 0xffff0000, v35
	s_waitcnt lgkmcnt(6)
	v_pk_fma_f32 v[2:3], v[102:103], v[2:3], v[118:119]
	v_cvt_pk_bf16_f32 v116, v2, v3
	global_store_dword v20, v116, s[6:7]
	v_lshlrev_b32_e32 v118, 16, v36
	v_and_b32_e32 v119, 0xffff0000, v36
	s_waitcnt lgkmcnt(5)
	v_pk_fma_f32 v[2:3], v[104:105], v[2:3], v[118:119]
	v_cvt_pk_bf16_f32 v117, v2, v3
	global_store_dword v21, v117, s[6:7]
	v_lshlrev_b32_e32 v118, 16, v37
	v_and_b32_e32 v119, 0xffff0000, v37
	s_waitcnt lgkmcnt(4)
	v_pk_fma_f32 v[2:3], v[106:107], v[2:3], v[118:119]
	v_cvt_pk_bf16_f32 v116, v2, v3
	global_store_dword v22, v116, s[6:7]
	v_lshlrev_b32_e32 v118, 16, v38
	v_and_b32_e32 v119, 0xffff0000, v38
	s_waitcnt lgkmcnt(3)
	v_pk_fma_f32 v[2:3], v[108:109], v[2:3], v[118:119]
	v_cvt_pk_bf16_f32 v117, v2, v3
	global_store_dword v23, v117, s[6:7]
	v_lshlrev_b32_e32 v118, 16, v39
	v_and_b32_e32 v119, 0xffff0000, v39
	s_waitcnt lgkmcnt(2)
	v_pk_fma_f32 v[2:3], v[110:111], v[2:3], v[118:119]
	v_cvt_pk_bf16_f32 v116, v2, v3
	global_store_dword v24, v116, s[6:7]
	v_lshlrev_b32_e32 v118, 16, v40
	v_and_b32_e32 v119, 0xffff0000, v40
	s_waitcnt lgkmcnt(1)
	v_pk_fma_f32 v[2:3], v[112:113], v[2:3], v[118:119]
	v_cvt_pk_bf16_f32 v117, v2, v3
	global_store_dword v25, v117, s[6:7]
	v_lshlrev_b32_e32 v118, 16, v41
	v_and_b32_e32 v119, 0xffff0000, v41
	s_waitcnt lgkmcnt(0)
	v_pk_fma_f32 v[2:3], v[114:115], v[2:3], v[118:119]
	s_add_u32 s6, s6, 0x400000
	s_addc_u32 s7, s7, 0
	v_add_u32_e32 v9, 0x2000, v9
	s_mov_b32 s1, 4
; #define SCAN_LOAD(uv, cb) do { _Pragma("unroll") for (int i = 0; i < 16; ++i) uv[i] = *(const u32x2*)(ut + (size_t)((cb) + i) * 131072); } while (0)
; __device__ __forceinline__ void scan_task(const Params& p, int l, int j, LAS unsigned char* lds) {
;     ...
;     for (int c0 = 0; c0 < 256; c0 += 32) {
;         SCAN_LOAD(uvB, c0 + 16);
;         SCAN_STEP(uvA, c0);
;         if (c0 + 32 < 256) SCAN_LOAD(uvA, c0 + 32);
;         SCAN_STEP(uvB, c0 + 16);
;     }
.Lscan_loop:
	global_load_dword v26, v10, s[16:17]
	global_load_dword v27, v11, s[16:17]
	global_load_dword v28, v12, s[16:17]
	global_load_dword v29, v13, s[16:17]
	global_load_dword v30, v14, s[16:17]
	global_load_dword v31, v15, s[16:17]
	global_load_dword v32, v16, s[16:17]
	global_load_dword v33, v17, s[16:17]
	global_load_dword v34, v18, s[16:17]
	global_load_dword v35, v19, s[16:17]
	global_load_dword v36, v20, s[16:17]
	global_load_dword v37, v21, s[16:17]
	global_load_dword v38, v22, s[16:17]
	global_load_dword v39, v23, s[16:17]
	global_load_dword v40, v24, s[16:17]
	global_load_dword v41, v25, s[16:17]
	s_add_u32 s16, s16, 0x400000
	s_addc_u32 s17, s17, 0
	ds_read_b64 v[100:101], v9
	ds_read_b64 v[102:103], v9 offset:512
	ds_read_b64 v[104:105], v9 offset:1024
	ds_read_b64 v[106:107], v9 offset:1536
	ds_read_b64 v[108:109], v9 offset:2048
	ds_read_b64 v[110:111], v9 offset:2560
	ds_read_b64 v[112:113], v9 offset:3072
	ds_read_b64 v[114:115], v9 offset:3584
	s_waitcnt vmcnt(48)
	v_cvt_pk_bf16_f32 v116, v2, v3
	global_store_dword v10, v116, s[6:7]
	v_lshlrev_b32_e32 v118, 16, v42
	v_and_b32_e32 v119, 0xffff0000, v42
	s_waitcnt lgkmcnt(7)
	v_pk_fma_f32 v[2:3], v[100:101], v[2:3], v[118:119]
	ds_read_b64 v[100:101], v9 offset:4096
	v_cvt_pk_bf16_f32 v117, v2, v3
	global_store_dword v11, v117, s[6:7]
	v_lshlrev_b32_e32 v118, 16, v43
	v_and_b32_e32 v119, 0xffff0000, v43
	s_waitcnt lgkmcnt(7)
	v_pk_fma_f32 v[2:3], v[102:103], v[2:3], v[118:119]
	ds_read_b64 v[102:103], v9 offset:4608
	v_cvt_pk_bf16_f32 v116, v2, v3
	global_store_dword v12, v116, s[6:7]
	v_lshlrev_b32_e32 v118, 16, v44
	v_and_b32_e32 v119, 0xffff0000, v44
	s_waitcnt lgkmcnt(7)
	v_pk_fma_f32 v[2:3], v[104:105], v[2:3], v[118:119]
	ds_read_b64 v[104:105], v9 offset:5120
	v_cvt_pk_bf16_f32 v117, v2, v3
	global_store_dword v13, v117, s[6:7]
	v_lshlrev_b32_e32 v118, 16, v45
	v_and_b32_e32 v119, 0xffff0000, v45
	s_waitcnt lgkmcnt(7)
	v_pk_fma_f32 v[2:3], v[106:107], v[2:3], v[118:119]
	ds_read_b64 v[106:107], v9 offset:5632
	v_cvt_pk_bf16_f32 v116, v2, v3
	global_store_dword v14, v116, s[6:7]
	v_lshlrev_b32_e32 v118, 16, v46
	v_and_b32_e32 v119, 0xffff0000, v46
	s_waitcnt lgkmcnt(7)
	v_pk_fma_f32 v[2:3], v[108:109], v[2:3], v[118:119]
	ds_read_b64 v[108:109], v9 offset:6144
	v_cvt_pk_bf16_f32 v117, v2, v3
	global_store_dword v15, v117, s[6:7]
	v_lshlrev_b32_e32 v118, 16, v47
	v_and_b32_e32 v119, 0xffff0000, v47
	s_waitcnt lgkmcnt(7)
	v_pk_fma_f32 v[2:3], v[110:111], v[2:3], v[118:119]
	ds_read_b64 v[110:111], v9 offset:6656
	v_cvt_pk_bf16_f32 v116, v2, v3
	global_store_dword v16, v116, s[6:7]
	v_lshlrev_b32_e32 v118, 16, v48
	v_and_b32_e32 v119, 0xffff0000, v48
	s_waitcnt lgkmcnt(7)
	v_pk_fma_f32 v[2:3], v[112:113], v[2:3], v[118:119]
	ds_read_b64 v[112:113], v9 offset:7168
	v_cvt_pk_bf16_f32 v117, v2, v3
	global_store_dword v17, v117, s[6:7]
	v_lshlrev_b32_e32 v118, 16, v49
	v_and_b32_e32 v119, 0xffff0000, v49
	s_waitcnt lgkmcnt(7)
	v_pk_fma_f32 v[2:3], v[114:115], v[2:3], v[118:119]
	ds_read_b64 v[114:115], v9 offset:7680
	v_cvt_pk_bf16_f32 v116, v2, v3
	global_store_dword v18, v116, s[6:7]
	v_lshlrev_b32_e32 v118, 16, v50
	v_and_b32_e32 v119, 0xffff0000, v50
	s_waitcnt lgkmcnt(7)
	v_pk_fma_f32 v[2:3], v[100:101], v[2:3], v[118:119]
	v_cvt_pk_bf16_f32 v117, v2, v3
	global_store_dword v19, v117, s[6:7]
	v_lshlrev_b32_e32 v118, 16, v51
	v_and_b32_e32 v119, 0xffff0000, v51
	s_waitcnt lgkmcnt(6)
	v_pk_fma_f32 v[2:3], v[102:103], v[2:3], v[118:119]
	v_cvt_pk_bf16_f32 v116, v2, v3
	global_store_dword v20, v116, s[6:7]
	v_lshlrev_b32_e32 v118, 16, v52
	v_and_b32_e32 v119, 0xffff0000, v52
	s_waitcnt lgkmcnt(5)
	v_pk_fma_f32 v[2:3], v[104:105], v[2:3], v[118:119]
	v_cvt_pk_bf16_f32 v117, v2, v3
	global_store_dword v21, v117, s[6:7]
	v_lshlrev_b32_e32 v118, 16, v53
	v_and_b32_e32 v119, 0xffff0000, v53
	s_waitcnt lgkmcnt(4)
	v_pk_fma_f32 v[2:3], v[106:107], v[2:3], v[118:119]
	v_cvt_pk_bf16_f32 v116, v2, v3
	global_store_dword v22, v116, s[6:7]
	v_lshlrev_b32_e32 v118, 16, v54
	v_and_b32_e32 v119, 0xffff0000, v54
	s_waitcnt lgkmcnt(3)
	v_pk_fma_f32 v[2:3], v[108:109], v[2:3], v[118:119]
	v_cvt_pk_bf16_f32 v117, v2, v3
	global_store_dword v23, v117, s[6:7]
	v_lshlrev_b32_e32 v118, 16, v55
	v_and_b32_e32 v119, 0xffff0000, v55
	s_waitcnt lgkmcnt(2)
	v_pk_fma_f32 v[2:3], v[110:111], v[2:3], v[118:119]
	v_cvt_pk_bf16_f32 v116, v2, v3
	global_store_dword v24, v116, s[6:7]
	v_lshlrev_b32_e32 v118, 16, v56
	v_and_b32_e32 v119, 0xffff0000, v56
	s_waitcnt lgkmcnt(1)
	v_pk_fma_f32 v[2:3], v[112:113], v[2:3], v[118:119]
	v_cvt_pk_bf16_f32 v117, v2, v3
	global_store_dword v25, v117, s[6:7]
	v_lshlrev_b32_e32 v118, 16, v57
	v_and_b32_e32 v119, 0xffff0000, v57
	s_waitcnt lgkmcnt(0)
	v_pk_fma_f32 v[2:3], v[114:115], v[2:3], v[118:119]
	s_add_u32 s6, s6, 0x400000
	s_addc_u32 s7, s7, 0
	v_add_u32_e32 v9, 0x2000, v9
	global_load_dword v42, v10, s[16:17]
	global_load_dword v43, v11, s[16:17]
	global_load_dword v44, v12, s[16:17]
	global_load_dword v45, v13, s[16:17]
	global_load_dword v46, v14, s[16:17]
	global_load_dword v47, v15, s[16:17]
	global_load_dword v48, v16, s[16:17]
	global_load_dword v49, v17, s[16:17]
	global_load_dword v50, v18, s[16:17]
	global_load_dword v51, v19, s[16:17]
	global_load_dword v52, v20, s[16:17]
	global_load_dword v53, v21, s[16:17]
	global_load_dword v54, v22, s[16:17]
	global_load_dword v55, v23, s[16:17]
	global_load_dword v56, v24, s[16:17]
	global_load_dword v57, v25, s[16:17]
	s_add_u32 s16, s16, 0x400000
	s_addc_u32 s17, s17, 0
	ds_read_b64 v[100:101], v9
	ds_read_b64 v[102:103], v9 offset:512
	ds_read_b64 v[104:105], v9 offset:1024
	ds_read_b64 v[106:107], v9 offset:1536
	ds_read_b64 v[108:109], v9 offset:2048
	ds_read_b64 v[110:111], v9 offset:2560
	ds_read_b64 v[112:113], v9 offset:3072
	ds_read_b64 v[114:115], v9 offset:3584
	s_waitcnt vmcnt(48)
; #define SCAN_LOAD(uv, cb) do { _Pragma("unroll") for (int i = 0; i < 16; ++i) uv[i] = *(const u32x2*)(ut + (size_t)((cb) + i) * 131072); } while (0)
; __device__ __forceinline__ void scan_task(const Params& p, int l, int j, LAS unsigned char* lds) {
;     ...
;     for (int c0 = 0; c0 < 256; c0 += 32) {
;         SCAN_LOAD(uvB, c0 + 16);
;         SCAN_STEP(uvA, c0);
;         if (c0 + 32 < 256) SCAN_LOAD(uvA, c0 + 32);
;         SCAN_STEP(uvB, c0 + 16);
;     }
	v_cvt_pk_bf16_f32 v116, v2, v3
	global_store_dword v10, v116, s[6:7]
	v_lshlrev_b32_e32 v118, 16, v58
	v_and_b32_e32 v119, 0xffff0000, v58
	s_waitcnt lgkmcnt(7)
	v_pk_fma_f32 v[2:3], v[100:101], v[2:3], v[118:119]
	ds_read_b64 v[100:101], v9 offset:4096
	v_cvt_pk_bf16_f32 v117, v2, v3
	global_store_dword v11, v117, s[6:7]
	v_lshlrev_b32_e32 v118, 16, v59
	v_and_b32_e32 v119, 0xffff0000, v59
	s_waitcnt lgkmcnt(7)
	v_pk_fma_f32 v[2:3], v[102:103], v[2:3], v[118:119]
	ds_read_b64 v[102:103], v9 offset:4608
	v_cvt_pk_bf16_f32 v116, v2, v3
	global_store_dword v12, v116, s[6:7]
	v_lshlrev_b32_e32 v118, 16, v60
	v_and_b32_e32 v119, 0xffff0000, v60
	s_waitcnt lgkmcnt(7)
	v_pk_fma_f32 v[2:3], v[104:105], v[2:3], v[118:119]
	ds_read_b64 v[104:105], v9 offset:5120
	v_cvt_pk_bf16_f32 v117, v2, v3
	global_store_dword v13, v117, s[6:7]
	v_lshlrev_b32_e32 v118, 16, v61
	v_and_b32_e32 v119, 0xffff0000, v61
	s_waitcnt lgkmcnt(7)
	v_pk_fma_f32 v[2:3], v[106:107], v[2:3], v[118:119]
	ds_read_b64 v[106:107], v9 offset:5632
	v_cvt_pk_bf16_f32 v116, v2, v3
	global_store_dword v14, v116, s[6:7]
	v_lshlrev_b32_e32 v118, 16, v62
	v_and_b32_e32 v119, 0xffff0000, v62
	s_waitcnt lgkmcnt(7)
	v_pk_fma_f32 v[2:3], v[108:109], v[2:3], v[118:119]
	ds_read_b64 v[108:109], v9 offset:6144
	v_cvt_pk_bf16_f32 v117, v2, v3
	global_store_dword v15, v117, s[6:7]
	v_lshlrev_b32_e32 v118, 16, v63
	v_and_b32_e32 v119, 0xffff0000, v63
	s_waitcnt lgkmcnt(7)
	v_pk_fma_f32 v[2:3], v[110:111], v[2:3], v[118:119]
	ds_read_b64 v[110:111], v9 offset:6656
	v_cvt_pk_bf16_f32 v116, v2, v3
	global_store_dword v16, v116, s[6:7]
	v_lshlrev_b32_e32 v118, 16, v64
	v_and_b32_e32 v119, 0xffff0000, v64
	s_waitcnt lgkmcnt(7)
	v_pk_fma_f32 v[2:3], v[112:113], v[2:3], v[118:119]
	ds_read_b64 v[112:113], v9 offset:7168
	v_cvt_pk_bf16_f32 v117, v2, v3
	global_store_dword v17, v117, s[6:7]
	v_lshlrev_b32_e32 v118, 16, v65
	v_and_b32_e32 v119, 0xffff0000, v65
	s_waitcnt lgkmcnt(7)
	v_pk_fma_f32 v[2:3], v[114:115], v[2:3], v[118:119]
	ds_read_b64 v[114:115], v9 offset:7680
	v_cvt_pk_bf16_f32 v116, v2, v3
	global_store_dword v18, v116, s[6:7]
	v_lshlrev_b32_e32 v118, 16, v66
	v_and_b32_e32 v119, 0xffff0000, v66
	s_waitcnt lgkmcnt(7)
	v_pk_fma_f32 v[2:3], v[100:101], v[2:3], v[118:119]
	v_cvt_pk_bf16_f32 v117, v2, v3
	global_store_dword v19, v117, s[6:7]
	v_lshlrev_b32_e32 v118, 16, v67
	v_and_b32_e32 v119, 0xffff0000, v67
	s_waitcnt lgkmcnt(6)
	v_pk_fma_f32 v[2:3], v[102:103], v[2:3], v[118:119]
	v_cvt_pk_bf16_f32 v116, v2, v3
	global_store_dword v20, v116, s[6:7]
	v_lshlrev_b32_e32 v118, 16, v68
	v_and_b32_e32 v119, 0xffff0000, v68
	s_waitcnt lgkmcnt(5)
	v_pk_fma_f32 v[2:3], v[104:105], v[2:3], v[118:119]
	v_cvt_pk_bf16_f32 v117, v2, v3
	global_store_dword v21, v117, s[6:7]
	v_lshlrev_b32_e32 v118, 16, v69
	v_and_b32_e32 v119, 0xffff0000, v69
	s_waitcnt lgkmcnt(4)
	v_pk_fma_f32 v[2:3], v[106:107], v[2:3], v[118:119]
	v_cvt_pk_bf16_f32 v116, v2, v3
	global_store_dword v22, v116, s[6:7]
	v_lshlrev_b32_e32 v118, 16, v70
	v_and_b32_e32 v119, 0xffff0000, v70
	s_waitcnt lgkmcnt(3)
	v_pk_fma_f32 v[2:3], v[108:109], v[2:3], v[118:119]
	v_cvt_pk_bf16_f32 v117, v2, v3
	global_store_dword v23, v117, s[6:7]
	v_lshlrev_b32_e32 v118, 16, v71
	v_and_b32_e32 v119, 0xffff0000, v71
	s_waitcnt lgkmcnt(2)
	v_pk_fma_f32 v[2:3], v[110:111], v[2:3], v[118:119]
	v_cvt_pk_bf16_f32 v116, v2, v3
	global_store_dword v24, v116, s[6:7]
	v_lshlrev_b32_e32 v118, 16, v72
	v_and_b32_e32 v119, 0xffff0000, v72
	s_waitcnt lgkmcnt(1)
	v_pk_fma_f32 v[2:3], v[112:113], v[2:3], v[118:119]
	v_cvt_pk_bf16_f32 v117, v2, v3
	global_store_dword v25, v117, s[6:7]
	v_lshlrev_b32_e32 v118, 16, v73
	v_and_b32_e32 v119, 0xffff0000, v73
	s_waitcnt lgkmcnt(0)
	v_pk_fma_f32 v[2:3], v[114:115], v[2:3], v[118:119]
	s_add_u32 s6, s6, 0x400000
	s_addc_u32 s7, s7, 0
	v_add_u32_e32 v9, 0x2000, v9
	global_load_dword v58, v10, s[16:17]
	global_load_dword v59, v11, s[16:17]
	global_load_dword v60, v12, s[16:17]
	global_load_dword v61, v13, s[16:17]
	global_load_dword v62, v14, s[16:17]
	global_load_dword v63, v15, s[16:17]
	global_load_dword v64, v16, s[16:17]
	global_load_dword v65, v17, s[16:17]
	global_load_dword v66, v18, s[16:17]
	global_load_dword v67, v19, s[16:17]
	global_load_dword v68, v20, s[16:17]
	global_load_dword v69, v21, s[16:17]
	global_load_dword v70, v22, s[16:17]
	global_load_dword v71, v23, s[16:17]
	global_load_dword v72, v24, s[16:17]
	global_load_dword v73, v25, s[16:17]
	s_add_u32 s16, s16, 0x400000
	s_addc_u32 s17, s17, 0
	ds_read_b64 v[100:101], v9
	ds_read_b64 v[102:103], v9 offset:512
	ds_read_b64 v[104:105], v9 offset:1024
	ds_read_b64 v[106:107], v9 offset:1536
	ds_read_b64 v[108:109], v9 offset:2048
	ds_read_b64 v[110:111], v9 offset:2560
	ds_read_b64 v[112:113], v9 offset:3072
	ds_read_b64 v[114:115], v9 offset:3584
	s_waitcnt vmcnt(48)
	v_cvt_pk_bf16_f32 v116, v2, v3
	global_store_dword v10, v116, s[6:7]
	v_lshlrev_b32_e32 v118, 16, v26
	v_and_b32_e32 v119, 0xffff0000, v26
	s_waitcnt lgkmcnt(7)
	v_pk_fma_f32 v[2:3], v[100:101], v[2:3], v[118:119]
	ds_read_b64 v[100:101], v9 offset:4096
	v_cvt_pk_bf16_f32 v117, v2, v3
	global_store_dword v11, v117, s[6:7]
	v_lshlrev_b32_e32 v118, 16, v27
	v_and_b32_e32 v119, 0xffff0000, v27
	s_waitcnt lgkmcnt(7)
	v_pk_fma_f32 v[2:3], v[102:103], v[2:3], v[118:119]
	ds_read_b64 v[102:103], v9 offset:4608
	v_cvt_pk_bf16_f32 v116, v2, v3
	global_store_dword v12, v116, s[6:7]
	v_lshlrev_b32_e32 v118, 16, v28
	v_and_b32_e32 v119, 0xffff0000, v28
	s_waitcnt lgkmcnt(7)
	v_pk_fma_f32 v[2:3], v[104:105], v[2:3], v[118:119]
	ds_read_b64 v[104:105], v9 offset:5120
	v_cvt_pk_bf16_f32 v117, v2, v3
	global_store_dword v13, v117, s[6:7]
	v_lshlrev_b32_e32 v118, 16, v29
	v_and_b32_e32 v119, 0xffff0000, v29
	s_waitcnt lgkmcnt(7)
; #define SCAN_LOAD(uv, cb) do { _Pragma("unroll") for (int i = 0; i < 16; ++i) uv[i] = *(const u32x2*)(ut + (size_t)((cb) + i) * 131072); } while (0)
; __device__ __forceinline__ void scan_task(const Params& p, int l, int j, LAS unsigned char* lds) {
;     ...
;     for (int c0 = 0; c0 < 256; c0 += 32) {
;         SCAN_LOAD(uvB, c0 + 16);
;         SCAN_STEP(uvA, c0);
;         if (c0 + 32 < 256) SCAN_LOAD(uvA, c0 + 32);
;         SCAN_STEP(uvB, c0 + 16);
;     }
	v_pk_fma_f32 v[2:3], v[106:107], v[2:3], v[118:119]
	ds_read_b64 v[106:107], v9 offset:5632
	v_cvt_pk_bf16_f32 v116, v2, v3
	global_store_dword v14, v116, s[6:7]
	v_lshlrev_b32_e32 v118, 16, v30
	v_and_b32_e32 v119, 0xffff0000, v30
	s_waitcnt lgkmcnt(7)
	v_pk_fma_f32 v[2:3], v[108:109], v[2:3], v[118:119]
	ds_read_b64 v[108:109], v9 offset:6144
	v_cvt_pk_bf16_f32 v117, v2, v3
	global_store_dword v15, v117, s[6:7]
	v_lshlrev_b32_e32 v118, 16, v31
	v_and_b32_e32 v119, 0xffff0000, v31
	s_waitcnt lgkmcnt(7)
	v_pk_fma_f32 v[2:3], v[110:111], v[2:3], v[118:119]
	ds_read_b64 v[110:111], v9 offset:6656
	v_cvt_pk_bf16_f32 v116, v2, v3
	global_store_dword v16, v116, s[6:7]
	v_lshlrev_b32_e32 v118, 16, v32
	v_and_b32_e32 v119, 0xffff0000, v32
	s_waitcnt lgkmcnt(7)
	v_pk_fma_f32 v[2:3], v[112:113], v[2:3], v[118:119]
	ds_read_b64 v[112:113], v9 offset:7168
	v_cvt_pk_bf16_f32 v117, v2, v3
	global_store_dword v17, v117, s[6:7]
	v_lshlrev_b32_e32 v118, 16, v33
	v_and_b32_e32 v119, 0xffff0000, v33
	s_waitcnt lgkmcnt(7)
	v_pk_fma_f32 v[2:3], v[114:115], v[2:3], v[118:119]
	ds_read_b64 v[114:115], v9 offset:7680
	v_cvt_pk_bf16_f32 v116, v2, v3
	global_store_dword v18, v116, s[6:7]
	v_lshlrev_b32_e32 v118, 16, v34
	v_and_b32_e32 v119, 0xffff0000, v34
	s_waitcnt lgkmcnt(7)
	v_pk_fma_f32 v[2:3], v[100:101], v[2:3], v[118:119]
	v_cvt_pk_bf16_f32 v117, v2, v3
	global_store_dword v19, v117, s[6:7]
	v_lshlrev_b32_e32 v118, 16, v35
	v_and_b32_e32 v119, 0xffff0000, v35
	s_waitcnt lgkmcnt(6)
	v_pk_fma_f32 v[2:3], v[102:103], v[2:3], v[118:119]
	v_cvt_pk_bf16_f32 v116, v2, v3
	global_store_dword v20, v116, s[6:7]
	v_lshlrev_b32_e32 v118, 16, v36
	v_and_b32_e32 v119, 0xffff0000, v36
	s_waitcnt lgkmcnt(5)
	v_pk_fma_f32 v[2:3], v[104:105], v[2:3], v[118:119]
	v_cvt_pk_bf16_f32 v117, v2, v3
	global_store_dword v21, v117, s[6:7]
	v_lshlrev_b32_e32 v118, 16, v37
	v_and_b32_e32 v119, 0xffff0000, v37
	s_waitcnt lgkmcnt(4)
	v_pk_fma_f32 v[2:3], v[106:107], v[2:3], v[118:119]
	v_cvt_pk_bf16_f32 v116, v2, v3
	global_store_dword v22, v116, s[6:7]
	v_lshlrev_b32_e32 v118, 16, v38
	v_and_b32_e32 v119, 0xffff0000, v38
	s_waitcnt lgkmcnt(3)
	v_pk_fma_f32 v[2:3], v[108:109], v[2:3], v[118:119]
	v_cvt_pk_bf16_f32 v117, v2, v3
	global_store_dword v23, v117, s[6:7]
	v_lshlrev_b32_e32 v118, 16, v39
	v_and_b32_e32 v119, 0xffff0000, v39
	s_waitcnt lgkmcnt(2)
	v_pk_fma_f32 v[2:3], v[110:111], v[2:3], v[118:119]
	v_cvt_pk_bf16_f32 v116, v2, v3
	global_store_dword v24, v116, s[6:7]
	v_lshlrev_b32_e32 v118, 16, v40
	v_and_b32_e32 v119, 0xffff0000, v40
	s_waitcnt lgkmcnt(1)
	v_pk_fma_f32 v[2:3], v[112:113], v[2:3], v[118:119]
	v_cvt_pk_bf16_f32 v117, v2, v3
	global_store_dword v25, v117, s[6:7]
	v_lshlrev_b32_e32 v118, 16, v41
	v_and_b32_e32 v119, 0xffff0000, v41
	s_waitcnt lgkmcnt(0)
	v_pk_fma_f32 v[2:3], v[114:115], v[2:3], v[118:119]
	s_add_u32 s6, s6, 0x400000
	s_addc_u32 s7, s7, 0
	v_add_u32_e32 v9, 0x2000, v9
	s_sub_u32 s1, s1, 1
	s_cmp_lg_u32 s1, 0
	s_cbranch_scc1 .Lscan_loop
	global_load_dword v26, v10, s[16:17]
	global_load_dword v27, v11, s[16:17]
	global_load_dword v28, v12, s[16:17]
	global_load_dword v29, v13, s[16:17]
	global_load_dword v30, v14, s[16:17]
	global_load_dword v31, v15, s[16:17]
	global_load_dword v32, v16, s[16:17]
	global_load_dword v33, v17, s[16:17]
	global_load_dword v34, v18, s[16:17]
	global_load_dword v35, v19, s[16:17]
	global_load_dword v36, v20, s[16:17]
	global_load_dword v37, v21, s[16:17]
	global_load_dword v38, v22, s[16:17]
	global_load_dword v39, v23, s[16:17]
	global_load_dword v40, v24, s[16:17]
	global_load_dword v41, v25, s[16:17]
	s_add_u32 s16, s16, 0x400000
	s_addc_u32 s17, s17, 0
	ds_read_b64 v[100:101], v9
	ds_read_b64 v[102:103], v9 offset:512
	ds_read_b64 v[104:105], v9 offset:1024
	ds_read_b64 v[106:107], v9 offset:1536
	ds_read_b64 v[108:109], v9 offset:2048
	ds_read_b64 v[110:111], v9 offset:2560
	ds_read_b64 v[112:113], v9 offset:3072
	ds_read_b64 v[114:115], v9 offset:3584
	s_waitcnt vmcnt(48)
	v_cvt_pk_bf16_f32 v116, v2, v3
	global_store_dword v10, v116, s[6:7]
	v_lshlrev_b32_e32 v118, 16, v42
	v_and_b32_e32 v119, 0xffff0000, v42
	s_waitcnt lgkmcnt(7)
	v_pk_fma_f32 v[2:3], v[100:101], v[2:3], v[118:119]
	ds_read_b64 v[100:101], v9 offset:4096
	v_cvt_pk_bf16_f32 v117, v2, v3
	global_store_dword v11, v117, s[6:7]
	v_lshlrev_b32_e32 v118, 16, v43
	v_and_b32_e32 v119, 0xffff0000, v43
	s_waitcnt lgkmcnt(7)
	v_pk_fma_f32 v[2:3], v[102:103], v[2:3], v[118:119]
	ds_read_b64 v[102:103], v9 offset:4608
	v_cvt_pk_bf16_f32 v116, v2, v3
	global_store_dword v12, v116, s[6:7]
	v_lshlrev_b32_e32 v118, 16, v44
	v_and_b32_e32 v119, 0xffff0000, v44
	s_waitcnt lgkmcnt(7)
	v_pk_fma_f32 v[2:3], v[104:105], v[2:3], v[118:119]
	ds_read_b64 v[104:105], v9 offset:5120
	v_cvt_pk_bf16_f32 v117, v2, v3
	global_store_dword v13, v117, s[6:7]
	v_lshlrev_b32_e32 v118, 16, v45
	v_and_b32_e32 v119, 0xffff0000, v45
	s_waitcnt lgkmcnt(7)
	v_pk_fma_f32 v[2:3], v[106:107], v[2:3], v[118:119]
	ds_read_b64 v[106:107], v9 offset:5632
	v_cvt_pk_bf16_f32 v116, v2, v3
	global_store_dword v14, v116, s[6:7]
	v_lshlrev_b32_e32 v118, 16, v46
	v_and_b32_e32 v119, 0xffff0000, v46
	s_waitcnt lgkmcnt(7)
	v_pk_fma_f32 v[2:3], v[108:109], v[2:3], v[118:119]
	ds_read_b64 v[108:109], v9 offset:6144
	v_cvt_pk_bf16_f32 v117, v2, v3
	global_store_dword v15, v117, s[6:7]
	v_lshlrev_b32_e32 v118, 16, v47
	v_and_b32_e32 v119, 0xffff0000, v47
	s_waitcnt lgkmcnt(7)
	v_pk_fma_f32 v[2:3], v[110:111], v[2:3], v[118:119]
	ds_read_b64 v[110:111], v9 offset:6656
	v_cvt_pk_bf16_f32 v116, v2, v3
	global_store_dword v16, v116, s[6:7]
	v_lshlrev_b32_e32 v118, 16, v48
	v_and_b32_e32 v119, 0xffff0000, v48
	s_waitcnt lgkmcnt(7)
; #define SCAN_LOAD(uv, cb) do { _Pragma("unroll") for (int i = 0; i < 16; ++i) uv[i] = *(const u32x2*)(ut + (size_t)((cb) + i) * 131072); } while (0)
; __device__ __forceinline__ void scan_task(const Params& p, int l, int j, LAS unsigned char* lds) {
;     ...
;     for (int c0 = 0; c0 < 256; c0 += 32) {
;         SCAN_LOAD(uvB, c0 + 16);
;         SCAN_STEP(uvA, c0);
;         if (c0 + 32 < 256) SCAN_LOAD(uvA, c0 + 32);
;         SCAN_STEP(uvB, c0 + 16);
;     }
	v_pk_fma_f32 v[2:3], v[112:113], v[2:3], v[118:119]
	ds_read_b64 v[112:113], v9 offset:7168
	v_cvt_pk_bf16_f32 v117, v2, v3
	global_store_dword v17, v117, s[6:7]
	v_lshlrev_b32_e32 v118, 16, v49
	v_and_b32_e32 v119, 0xffff0000, v49
	s_waitcnt lgkmcnt(7)
	v_pk_fma_f32 v[2:3], v[114:115], v[2:3], v[118:119]
	ds_read_b64 v[114:115], v9 offset:7680
	v_cvt_pk_bf16_f32 v116, v2, v3
	global_store_dword v18, v116, s[6:7]
	v_lshlrev_b32_e32 v118, 16, v50
	v_and_b32_e32 v119, 0xffff0000, v50
	s_waitcnt lgkmcnt(7)
	v_pk_fma_f32 v[2:3], v[100:101], v[2:3], v[118:119]
	v_cvt_pk_bf16_f32 v117, v2, v3
	global_store_dword v19, v117, s[6:7]
	v_lshlrev_b32_e32 v118, 16, v51
	v_and_b32_e32 v119, 0xffff0000, v51
	s_waitcnt lgkmcnt(6)
	v_pk_fma_f32 v[2:3], v[102:103], v[2:3], v[118:119]
	v_cvt_pk_bf16_f32 v116, v2, v3
	global_store_dword v20, v116, s[6:7]
	v_lshlrev_b32_e32 v118, 16, v52
	v_and_b32_e32 v119, 0xffff0000, v52
	s_waitcnt lgkmcnt(5)
	v_pk_fma_f32 v[2:3], v[104:105], v[2:3], v[118:119]
	v_cvt_pk_bf16_f32 v117, v2, v3
	global_store_dword v21, v117, s[6:7]
	v_lshlrev_b32_e32 v118, 16, v53
	v_and_b32_e32 v119, 0xffff0000, v53
	s_waitcnt lgkmcnt(4)
	v_pk_fma_f32 v[2:3], v[106:107], v[2:3], v[118:119]
	v_cvt_pk_bf16_f32 v116, v2, v3
	global_store_dword v22, v116, s[6:7]
	v_lshlrev_b32_e32 v118, 16, v54
	v_and_b32_e32 v119, 0xffff0000, v54
	s_waitcnt lgkmcnt(3)
	v_pk_fma_f32 v[2:3], v[108:109], v[2:3], v[118:119]
	v_cvt_pk_bf16_f32 v117, v2, v3
	global_store_dword v23, v117, s[6:7]
	v_lshlrev_b32_e32 v118, 16, v55
	v_and_b32_e32 v119, 0xffff0000, v55
	s_waitcnt lgkmcnt(2)
	v_pk_fma_f32 v[2:3], v[110:111], v[2:3], v[118:119]
	v_cvt_pk_bf16_f32 v116, v2, v3
	global_store_dword v24, v116, s[6:7]
	v_lshlrev_b32_e32 v118, 16, v56
	v_and_b32_e32 v119, 0xffff0000, v56
	s_waitcnt lgkmcnt(1)
	v_pk_fma_f32 v[2:3], v[112:113], v[2:3], v[118:119]
	v_cvt_pk_bf16_f32 v117, v2, v3
	global_store_dword v25, v117, s[6:7]
	v_lshlrev_b32_e32 v118, 16, v57
	v_and_b32_e32 v119, 0xffff0000, v57
	s_waitcnt lgkmcnt(0)
	v_pk_fma_f32 v[2:3], v[114:115], v[2:3], v[118:119]
	s_add_u32 s6, s6, 0x400000
	s_addc_u32 s7, s7, 0
	v_add_u32_e32 v9, 0x2000, v9
	ds_read_b64 v[100:101], v9
	ds_read_b64 v[102:103], v9 offset:512
	ds_read_b64 v[104:105], v9 offset:1024
	ds_read_b64 v[106:107], v9 offset:1536
	ds_read_b64 v[108:109], v9 offset:2048
	ds_read_b64 v[110:111], v9 offset:2560
	ds_read_b64 v[112:113], v9 offset:3072
	ds_read_b64 v[114:115], v9 offset:3584
	s_waitcnt vmcnt(48)
	v_cvt_pk_bf16_f32 v116, v2, v3
	global_store_dword v10, v116, s[6:7]
	v_lshlrev_b32_e32 v118, 16, v58
	v_and_b32_e32 v119, 0xffff0000, v58
	s_waitcnt lgkmcnt(7)
	v_pk_fma_f32 v[2:3], v[100:101], v[2:3], v[118:119]
	ds_read_b64 v[100:101], v9 offset:4096
	v_cvt_pk_bf16_f32 v117, v2, v3
	global_store_dword v11, v117, s[6:7]
	v_lshlrev_b32_e32 v118, 16, v59
	v_and_b32_e32 v119, 0xffff0000, v59
	s_waitcnt lgkmcnt(7)
	v_pk_fma_f32 v[2:3], v[102:103], v[2:3], v[118:119]
	ds_read_b64 v[102:103], v9 offset:4608
	v_cvt_pk_bf16_f32 v116, v2, v3
	global_store_dword v12, v116, s[6:7]
	v_lshlrev_b32_e32 v118, 16, v60
	v_and_b32_e32 v119, 0xffff0000, v60
	s_waitcnt lgkmcnt(7)
	v_pk_fma_f32 v[2:3], v[104:105], v[2:3], v[118:119]
	ds_read_b64 v[104:105], v9 offset:5120
	v_cvt_pk_bf16_f32 v117, v2, v3
	global_store_dword v13, v117, s[6:7]
	v_lshlrev_b32_e32 v118, 16, v61
	v_and_b32_e32 v119, 0xffff0000, v61
	s_waitcnt lgkmcnt(7)
	v_pk_fma_f32 v[2:3], v[106:107], v[2:3], v[118:119]
	ds_read_b64 v[106:107], v9 offset:5632
	v_cvt_pk_bf16_f32 v116, v2, v3
	global_store_dword v14, v116, s[6:7]
	v_lshlrev_b32_e32 v118, 16, v62
	v_and_b32_e32 v119, 0xffff0000, v62
	s_waitcnt lgkmcnt(7)
	v_pk_fma_f32 v[2:3], v[108:109], v[2:3], v[118:119]
	ds_read_b64 v[108:109], v9 offset:6144
	v_cvt_pk_bf16_f32 v117, v2, v3
	global_store_dword v15, v117, s[6:7]
	v_lshlrev_b32_e32 v118, 16, v63
	v_and_b32_e32 v119, 0xffff0000, v63
	s_waitcnt lgkmcnt(7)
	v_pk_fma_f32 v[2:3], v[110:111], v[2:3], v[118:119]
	ds_read_b64 v[110:111], v9 offset:6656
	v_cvt_pk_bf16_f32 v116, v2, v3
	global_store_dword v16, v116, s[6:7]
	v_lshlrev_b32_e32 v118, 16, v64
	v_and_b32_e32 v119, 0xffff0000, v64
	s_waitcnt lgkmcnt(7)
	v_pk_fma_f32 v[2:3], v[112:113], v[2:3], v[118:119]
	ds_read_b64 v[112:113], v9 offset:7168
	v_cvt_pk_bf16_f32 v117, v2, v3
	global_store_dword v17, v117, s[6:7]
	v_lshlrev_b32_e32 v118, 16, v65
	v_and_b32_e32 v119, 0xffff0000, v65
	s_waitcnt lgkmcnt(7)
	v_pk_fma_f32 v[2:3], v[114:115], v[2:3], v[118:119]
	ds_read_b64 v[114:115], v9 offset:7680
	v_cvt_pk_bf16_f32 v116, v2, v3
	global_store_dword v18, v116, s[6:7]
	v_lshlrev_b32_e32 v118, 16, v66
	v_and_b32_e32 v119, 0xffff0000, v66
	s_waitcnt lgkmcnt(7)
	v_pk_fma_f32 v[2:3], v[100:101], v[2:3], v[118:119]
	v_cvt_pk_bf16_f32 v117, v2, v3
	global_store_dword v19, v117, s[6:7]
	v_lshlrev_b32_e32 v118, 16, v67
	v_and_b32_e32 v119, 0xffff0000, v67
	s_waitcnt lgkmcnt(6)
	v_pk_fma_f32 v[2:3], v[102:103], v[2:3], v[118:119]
	v_cvt_pk_bf16_f32 v116, v2, v3
	global_store_dword v20, v116, s[6:7]
	v_lshlrev_b32_e32 v118, 16, v68
	v_and_b32_e32 v119, 0xffff0000, v68
	s_waitcnt lgkmcnt(5)
	v_pk_fma_f32 v[2:3], v[104:105], v[2:3], v[118:119]
	v_cvt_pk_bf16_f32 v117, v2, v3
	global_store_dword v21, v117, s[6:7]
	v_lshlrev_b32_e32 v118, 16, v69
	v_and_b32_e32 v119, 0xffff0000, v69
	s_waitcnt lgkmcnt(4)
	v_pk_fma_f32 v[2:3], v[106:107], v[2:3], v[118:119]
	v_cvt_pk_bf16_f32 v116, v2, v3
	global_store_dword v22, v116, s[6:7]
	v_lshlrev_b32_e32 v118, 16, v70
	v_and_b32_e32 v119, 0xffff0000, v70
	s_waitcnt lgkmcnt(3)
; #define SCAN_LOAD(uv, cb) do { _Pragma("unroll") for (int i = 0; i < 16; ++i) uv[i] = *(const u32x2*)(ut + (size_t)((cb) + i) * 131072); } while (0)
; __device__ __forceinline__ void scan_task(const Params& p, int l, int j, LAS unsigned char* lds) {
;     ...
;     for (int c0 = 0; c0 < 256; c0 += 32) {
;         SCAN_LOAD(uvB, c0 + 16);
;         SCAN_STEP(uvA, c0);
;         if (c0 + 32 < 256) SCAN_LOAD(uvA, c0 + 32);
;         SCAN_STEP(uvB, c0 + 16);
;     }
;     ...
;     float* go = p.out + OFF_GSP + ((size_t)l * 4 + h) * 32768 + dk * 256 + dv;
; #pragma unroll
;     for (int i = 0; i < 4; ++i) go[i * 256] = S[i];
	v_pk_fma_f32 v[2:3], v[108:109], v[2:3], v[118:119]
	v_cvt_pk_bf16_f32 v117, v2, v3
	global_store_dword v23, v117, s[6:7]
	v_lshlrev_b32_e32 v118, 16, v71
	v_and_b32_e32 v119, 0xffff0000, v71
	s_waitcnt lgkmcnt(2)
	v_pk_fma_f32 v[2:3], v[110:111], v[2:3], v[118:119]
	v_cvt_pk_bf16_f32 v116, v2, v3
	global_store_dword v24, v116, s[6:7]
	v_lshlrev_b32_e32 v118, 16, v72
	v_and_b32_e32 v119, 0xffff0000, v72
	s_waitcnt lgkmcnt(1)
	v_pk_fma_f32 v[2:3], v[112:113], v[2:3], v[118:119]
	v_cvt_pk_bf16_f32 v117, v2, v3
	global_store_dword v25, v117, s[6:7]
	v_lshlrev_b32_e32 v118, 16, v73
	v_and_b32_e32 v119, 0xffff0000, v73
	s_waitcnt lgkmcnt(0)
	v_pk_fma_f32 v[2:3], v[114:115], v[2:3], v[118:119]
	s_add_u32 s6, s6, 0x400000
	s_addc_u32 s7, s7, 0
	v_add_u32_e32 v9, 0x2000, v9
	ds_read_b64 v[100:101], v9
	ds_read_b64 v[102:103], v9 offset:512
	ds_read_b64 v[104:105], v9 offset:1024
	ds_read_b64 v[106:107], v9 offset:1536
	ds_read_b64 v[108:109], v9 offset:2048
	ds_read_b64 v[110:111], v9 offset:2560
	ds_read_b64 v[112:113], v9 offset:3072
	ds_read_b64 v[114:115], v9 offset:3584
	s_waitcnt vmcnt(32)
	v_cvt_pk_bf16_f32 v116, v2, v3
	global_store_dword v10, v116, s[6:7]
	v_lshlrev_b32_e32 v118, 16, v26
	v_and_b32_e32 v119, 0xffff0000, v26
	s_waitcnt lgkmcnt(7)
	v_pk_fma_f32 v[2:3], v[100:101], v[2:3], v[118:119]
	ds_read_b64 v[100:101], v9 offset:4096
	v_cvt_pk_bf16_f32 v117, v2, v3
	global_store_dword v11, v117, s[6:7]
	v_lshlrev_b32_e32 v118, 16, v27
	v_and_b32_e32 v119, 0xffff0000, v27
	s_waitcnt lgkmcnt(7)
	v_pk_fma_f32 v[2:3], v[102:103], v[2:3], v[118:119]
	ds_read_b64 v[102:103], v9 offset:4608
	v_cvt_pk_bf16_f32 v116, v2, v3
	global_store_dword v12, v116, s[6:7]
	v_lshlrev_b32_e32 v118, 16, v28
	v_and_b32_e32 v119, 0xffff0000, v28
	s_waitcnt lgkmcnt(7)
	v_pk_fma_f32 v[2:3], v[104:105], v[2:3], v[118:119]
	ds_read_b64 v[104:105], v9 offset:5120
	v_cvt_pk_bf16_f32 v117, v2, v3
	global_store_dword v13, v117, s[6:7]
	v_lshlrev_b32_e32 v118, 16, v29
	v_and_b32_e32 v119, 0xffff0000, v29
	s_waitcnt lgkmcnt(7)
	v_pk_fma_f32 v[2:3], v[106:107], v[2:3], v[118:119]
	ds_read_b64 v[106:107], v9 offset:5632
	v_cvt_pk_bf16_f32 v116, v2, v3
	global_store_dword v14, v116, s[6:7]
	v_lshlrev_b32_e32 v118, 16, v30
	v_and_b32_e32 v119, 0xffff0000, v30
	s_waitcnt lgkmcnt(7)
	v_pk_fma_f32 v[2:3], v[108:109], v[2:3], v[118:119]
	ds_read_b64 v[108:109], v9 offset:6144
	v_cvt_pk_bf16_f32 v117, v2, v3
	global_store_dword v15, v117, s[6:7]
	v_lshlrev_b32_e32 v118, 16, v31
	v_and_b32_e32 v119, 0xffff0000, v31
	s_waitcnt lgkmcnt(7)
	v_pk_fma_f32 v[2:3], v[110:111], v[2:3], v[118:119]
	ds_read_b64 v[110:111], v9 offset:6656
	v_cvt_pk_bf16_f32 v116, v2, v3
	global_store_dword v16, v116, s[6:7]
	v_lshlrev_b32_e32 v118, 16, v32
	v_and_b32_e32 v119, 0xffff0000, v32
	s_waitcnt lgkmcnt(7)
	v_pk_fma_f32 v[2:3], v[112:113], v[2:3], v[118:119]
	ds_read_b64 v[112:113], v9 offset:7168
	v_cvt_pk_bf16_f32 v117, v2, v3
	global_store_dword v17, v117, s[6:7]
	v_lshlrev_b32_e32 v118, 16, v33
	v_and_b32_e32 v119, 0xffff0000, v33
	s_waitcnt lgkmcnt(7)
	v_pk_fma_f32 v[2:3], v[114:115], v[2:3], v[118:119]
	ds_read_b64 v[114:115], v9 offset:7680
	v_cvt_pk_bf16_f32 v116, v2, v3
	global_store_dword v18, v116, s[6:7]
	v_lshlrev_b32_e32 v118, 16, v34
	v_and_b32_e32 v119, 0xffff0000, v34
	s_waitcnt lgkmcnt(7)
	v_pk_fma_f32 v[2:3], v[100:101], v[2:3], v[118:119]
	v_cvt_pk_bf16_f32 v117, v2, v3
	global_store_dword v19, v117, s[6:7]
	v_lshlrev_b32_e32 v118, 16, v35
	v_and_b32_e32 v119, 0xffff0000, v35
	s_waitcnt lgkmcnt(6)
	v_pk_fma_f32 v[2:3], v[102:103], v[2:3], v[118:119]
	v_cvt_pk_bf16_f32 v116, v2, v3
	global_store_dword v20, v116, s[6:7]
	v_lshlrev_b32_e32 v118, 16, v36
	v_and_b32_e32 v119, 0xffff0000, v36
	s_waitcnt lgkmcnt(5)
	v_pk_fma_f32 v[2:3], v[104:105], v[2:3], v[118:119]
	v_cvt_pk_bf16_f32 v117, v2, v3
	global_store_dword v21, v117, s[6:7]
	v_lshlrev_b32_e32 v118, 16, v37
	v_and_b32_e32 v119, 0xffff0000, v37
	s_waitcnt lgkmcnt(4)
	v_pk_fma_f32 v[2:3], v[106:107], v[2:3], v[118:119]
	v_cvt_pk_bf16_f32 v116, v2, v3
	global_store_dword v22, v116, s[6:7]
	v_lshlrev_b32_e32 v118, 16, v38
	v_and_b32_e32 v119, 0xffff0000, v38
	s_waitcnt lgkmcnt(3)
	v_pk_fma_f32 v[2:3], v[108:109], v[2:3], v[118:119]
	v_cvt_pk_bf16_f32 v117, v2, v3
	global_store_dword v23, v117, s[6:7]
	v_lshlrev_b32_e32 v118, 16, v39
	v_and_b32_e32 v119, 0xffff0000, v39
	s_waitcnt lgkmcnt(2)
	v_pk_fma_f32 v[2:3], v[110:111], v[2:3], v[118:119]
	v_cvt_pk_bf16_f32 v116, v2, v3
	global_store_dword v24, v116, s[6:7]
	v_lshlrev_b32_e32 v118, 16, v40
	v_and_b32_e32 v119, 0xffff0000, v40
	s_waitcnt lgkmcnt(1)
	v_pk_fma_f32 v[2:3], v[112:113], v[2:3], v[118:119]
	v_cvt_pk_bf16_f32 v117, v2, v3
	global_store_dword v25, v117, s[6:7]
	v_lshlrev_b32_e32 v118, 16, v41
	v_and_b32_e32 v119, 0xffff0000, v41
	s_waitcnt lgkmcnt(0)
	v_pk_fma_f32 v[2:3], v[114:115], v[2:3], v[118:119]
	s_add_u32 s6, s6, 0x400000
	s_addc_u32 s7, s7, 0
	v_add_u32_e32 v9, 0x2000, v9
	v_readlane_b32 s16, v254, 59
	v_readlane_b32 s17, v254, 60
	s_lshl_b32 s0, s31, 19
	s_lshr_b32 s1, s23, 4
	s_lshl_b32 s1, s1, 17
	s_add_u32 s0, s0, s1
	s_and_b32 s1, s23, 15
	s_lshl_b32 s1, s1, 6
	s_add_u32 s0, s0, s1
	s_lshl_b32 s1, s2, 5
	s_add_u32 s0, s0, s1
	s_add_u32 s16, s16, s0
	s_addc_u32 s17, s17, 0
	v_and_b32_e32 v4, 63, v200
	v_lshlrev_b32_e32 v4, 11, v4
	v_lshrrev_b32_e32 v5, 6, v200
	v_lshl_add_u32 v4, v5, 2, v4
	s_nop 4
	global_store_dword v4, v2, s[16:17]
	global_store_dword v4, v3, s[16:17] offset:1024
	s_branch .LBB0_592
